# delta prompt producer: next chunk rows waited/unpacked at the next produce step (true one-chunk-ahead prefetch)
# speedup vs baseline: 1.0055x; 1.0055x over previous
; #define LAS __attribute__((address_space(3)))
; __device__ __forceinline__ void delta_unit(const Params& P, LAS unsigned char* lds, int li, bool sample, int b, int h, int half, const int tid) {
;     ...
;     if (wid >= 4) DN_LOADS(0);
;     for (int j = 0; j < NC + 2; ++j) {
;         if (wid >= 4) {
;             if (j < NC) {
;                 LAS float* qs = (LAS float*)(lds + (j & 1) * SET); LAS float* ks = qs + 2048; LAS float* vs = qs + 4096; LAS float* sc = qs + 8192;
;                 const int t0 = j * MX_CH + pw * 8;
;                 if (t0 < L) {
.LBB0_655:
	s_andn2_b64 vcc, exec, s[0:1]
	s_cbranch_vccnz .LBB0_660
	s_lshl_b32 s25, s14, 5
	s_cmp_ge_i32 s25, s15
	s_cbranch_scc1 .LBB0_660
	s_cmp_eq_u32 s14, 0
	s_cbranch_scc1 .Ldn_unpacked
	s_cmp_lt_u32 s14, 3
	s_cbranch_scc1 .Ldn_w0
	s_waitcnt vmcnt(8)
	s_branch .Ldn_wd

; __device__ __forceinline__ float silu_f(float x) { return x * fast_rcp(1.0f + __expf(-x)); }
; __device__ __forceinline__ void delta_unit(const Params& P, LAS unsigned char* lds, int li, bool sample, int b, int h, int half, const int tid) {
;     ...
;                     for (int i = 0; i < 8; ++i) {
;                         float q = cwq[0] * rq[i] + cwq[1] * rq[i + 1] + cwq[2] * rq[i + 2] + cwq[3] * rq[i + 3];
;                         float k = cwk[0] * rk[i] + cwk[1] * rk[i + 1] + cwk[2] * rk[i + 2] + cwk[3] * rk[i + 3];
;                         float v = cwv[0] * rv[i] + cwv[1] * rv[i + 1] + cwv[2] * rv[i + 2] + cwv[3] * rv[i + 3];
;                         q = silu_f(q); k = silu_f(k); v = silu_f(v);
;                         const float sq = wave_sum(q * q), sk = wave_sum(k * k);
;                         const int tok = pw * 8 + i;
;                         qs[tok * 64 + c] = q * rsqrtf(sq + EPS) * 0.125f; ks[tok * 64 + c] = k * rsqrtf(sk + EPS); vs[tok * 64 + c] = v;
;                     }
.Ldn_wd:
	v_mov_b32_e32 v0, 1.0
	v_mov_b32_e32 v2, 1.0
	v_mov_b32_e32 v3, 1.0
	v_mov_b32_e32 v25, 1.0
	v_mov_b32_e32 v24, v3
	v_lshlrev_b32_e32 v1, 16, v8
	v_mul_f32_e32 v95, v0, v1
	v_lshlrev_b32_e32 v5, 16, v10
	v_lshlrev_b32_e32 v4, 16, v9
	v_mov_b32_e32 v1, v2
	v_pk_mul_f32 v[12:13], v[0:1], v[4:5]
	v_lshlrev_b32_e32 v5, 16, v14
	v_lshlrev_b32_e32 v4, 16, v18
	v_pk_mul_f32 v[0:1], v[0:1], v[4:5]
	v_lshlrev_b32_e32 v4, 16, v15
	v_lshlrev_b32_e32 v5, 16, v19
	v_pk_mul_f32 v[52:53], v[2:3], v[4:5]
	v_lshlrev_b32_e32 v5, 16, v20
	v_lshlrev_b32_e32 v4, 16, v16
	v_lshlrev_b32_e32 v3, 16, v21
	v_lshlrev_b32_e32 v2, 16, v17
	v_pk_mul_f32 v[14:15], v[24:25], v[4:5]
	v_pk_mul_f32 v[2:3], v[24:25], v[2:3]
	v_lshlrev_b32_e32 v5, 16, v26
	v_lshlrev_b32_e32 v4, 16, v22
	v_mov_b32_e32 v24, v25
	v_pk_mul_f32 v[54:55], v[24:25], v[4:5] op_sel_hi:[0,1]
	v_lshlrev_b32_e32 v5, 16, v28
	v_lshlrev_b32_e32 v7, 16, v6
	v_lshlrev_b32_e32 v6, 16, v31
	v_lshlrev_b32_e32 v4, 16, v27
	v_pk_mul_f32 v[56:57], v[24:25], v[6:7] op_sel_hi:[0,1]
	v_lshlrev_b32_e32 v9, 16, v35
	v_lshlrev_b32_e32 v7, 16, v33
	v_lshlrev_b32_e32 v6, 16, v32
	v_pk_mul_f32 v[16:17], v[24:25], v[4:5] op_sel_hi:[0,1]
	v_lshlrev_b32_e32 v5, 16, v30
	v_lshlrev_b32_e32 v4, 16, v29
	v_pk_mul_f32 v[18:19], v[24:25], v[6:7] op_sel_hi:[0,1]
	v_lshlrev_b32_e32 v8, 16, v37
	v_pk_mul_f32 v[58:59], v[24:25], v[8:9] op_sel_hi:[0,1]
	v_lshlrev_b32_e32 v9, 16, v38
	v_lshlrev_b32_e32 v8, 16, v39
	v_lshlrev_b32_e32 v7, 16, v34
	v_lshlrev_b32_e32 v10, 16, v62
	v_lshlrev_b32_e32 v6, 16, v36
	v_pk_mul_f32 v[20:21], v[24:25], v[8:9] op_sel_hi:[0,1]
	v_lshlrev_b32_e32 v9, 16, v60
	v_lshlrev_b32_e32 v8, 16, v63
	v_mul_f32_e32 v22, v25, v10
	v_lshlrev_b32_e32 v10, 16, v64
	v_lshlrev_b32_e32 v27, 16, v61
	v_lshlrev_b32_e32 v26, 16, v65
	v_pk_mul_f32 v[4:5], v[24:25], v[4:5] op_sel_hi:[0,1]
	v_pk_mul_f32 v[6:7], v[24:25], v[6:7] op_sel_hi:[0,1]
	v_pk_mul_f32 v[8:9], v[24:25], v[8:9] op_sel_hi:[0,1]
	v_mul_f32_e32 v10, v25, v10
	v_pk_mul_f32 v[60:61], v[24:25], v[26:27] op_sel_hi:[0,1]
.Ldn_unpacked:
	s_waitcnt lgkmcnt(4)
	v_pk_mul_f32 v[24:25], v[46:47], v[12:13]
	v_pk_mul_f32 v[26:27], v[42:43], v[14:15]
	v_add_f32_e32 v24, v24, v25
	v_add_f32_e32 v24, v26, v24
	s_waitcnt lgkmcnt(3)
	v_add_f32_e32 v28, v27, v24
	v_pk_mul_f32 v[24:25], v[40:41], v[0:1]
	v_pk_mul_f32 v[26:27], v[44:45], v[2:3]
	v_add_f32_e32 v24, v24, v25
	v_add_f32_e32 v24, v26, v24
	v_add_f32_e32 v24, v27, v24
	v_mul_f32_e32 v26, 0xbfb8aa3b, v28
	v_exp_f32_e32 v26, v26
	v_mul_f32_e32 v27, 0xbfb8aa3b, v24
	v_exp_f32_e32 v27, v27
	v_mul_f32_e32 v25, v11, v95
	v_fmac_f32_e32 v25, v23, v52
	v_add_f32_e32 v26, 1.0, v26
	v_fmac_f32_e32 v25, v72, v53
	v_rcp_f32_e32 v26, v26
	v_add_f32_e32 v27, 1.0, v27
	v_fmac_f32_e32 v25, v73, v55
	v_rcp_f32_e32 v27, v27
	v_mul_f32_e32 v29, 0xbfb8aa3b, v25
	v_exp_f32_e32 v29, v29
	v_mul_f32_e32 v26, v28, v26
	v_mul_f32_e32 v34, v24, v27
	v_mul_f32_e32 v24, v26, v26
	v_add_f32_e32 v29, 1.0, v29
	v_rcp_f32_e32 v29, v29
	v_mov_b32_dpp v24, v24 quad_perm:[1,0,3,2] row_mask:0xf bank_mask:0xf bound_ctrl:1
	v_fmac_f32_e32 v24, v26, v26
	s_bitcmp1_b32 s14, 0
	s_cselect_b32 s0, 0x8100, 0
	v_add_f32_dpp v24, v24, v24 quad_perm:[2,3,0,1] row_mask:0xf bank_mask:0xf bound_ctrl:1
	s_add_i32 s26, s0, 0
	v_mul_f32_e32 v35, v25, v29
	v_add_f32_dpp v24, v24, v24 row_half_mirror row_mask:0xf bank_mask:0xf bound_ctrl:1
	v_mov_b32_e32 v28, v15
	v_mov_b32_e32 v29, v16
	v_add_f32_dpp v24, v24, v24 row_mirror row_mask:0xf bank_mask:0xf bound_ctrl:1
	v_pk_mul_f32 v[30:31], v[42:43], v[28:29]
	v_readlane_b32 s27, v24, 16
	v_readlane_b32 s30, v24, 48
	v_readlane_b32 s0, v24, 0
	v_readlane_b32 s1, v24, 32
	v_mov_b32_e32 v24, s27
	v_mov_b32_e32 v25, s30
	v_pk_add_f32 v[24:25], s[0:1], v[24:25]
	s_nop 0
	v_add_f32_e32 v25, v24, v25
	v_mul_f32_e32 v24, v34, v34
	v_add_f32_e32 v25, 0x358637bd, v25
	v_mul_f32_e32 v27, 0x4b800000, v25
	v_mov_b32_dpp v24, v24 quad_perm:[1,0,3,2] row_mask:0xf bank_mask:0xf bound_ctrl:1
	v_fmac_f32_e32 v24, v34, v34
	v_cmp_gt_f32_e32 vcc, s3, v25
	s_nop 0
	v_add_f32_dpp v24, v24, v24 quad_perm:[2,3,0,1] row_mask:0xf bank_mask:0xf bound_ctrl:1
	v_cndmask_b32_e32 v25, v25, v27, vcc
	v_rsq_f32_e32 v27, v25
	v_add_f32_dpp v24, v24, v24 row_half_mirror row_mask:0xf bank_mask:0xf bound_ctrl:1
	s_nop 1
	v_add_f32_dpp v24, v24, v24 row_mirror row_mask:0xf bank_mask:0xf bound_ctrl:1
	s_nop 0
	v_readlane_b32 s27, v24, 16
	v_readlane_b32 s30, v24, 48
	v_readlane_b32 s0, v24, 0
	v_readlane_b32 s1, v24, 32
	v_mov_b32_e32 v24, s27
	v_mov_b32_e32 v25, s30
	v_pk_add_f32 v[24:25], s[0:1], v[24:25]
	s_nop 0
	v_add_f32_e32 v24, v24, v25
	v_mul_f32_e32 v25, 0x45800000, v27
	v_add_f32_e32 v24, 0x358637bd, v24
	v_cndmask_b32_e32 v25, v27, v25, vcc
	v_mul_f32_e32 v27, 0x4b800000, v24
	v_cmp_gt_f32_e32 vcc, s3, v24
	s_nop 1
	v_cndmask_b32_e32 v24, v24, v27, vcc
	v_rsq_f32_e32 v27, v24
	v_mul_f32_e32 v24, v26, v25
	v_mul_f32_e32 v25, 0x3e000000, v24
	v_lshl_add_u32 v24, v82, 2, s26
	v_mul_f32_e32 v26, 0x45800000, v27
	v_cndmask_b32_e32 v36, v27, v26, vcc
	v_mov_b32_e32 v26, v13
	v_mov_b32_e32 v27, v14
	v_pk_mul_f32 v[26:27], v[46:47], v[26:27]
	v_mul_f32_e32 v34, v34, v36
	v_add_f32_e32 v26, v26, v27
	v_add_f32_e32 v26, v30, v26
	v_add_f32_e32 v37, v31, v26
	v_mov_b32_e32 v26, v1
	v_mov_b32_e32 v27, v2
	v_pk_mul_f32 v[26:27], v[40:41], v[26:27]
	v_mov_b32_e32 v30, v3
	v_mov_b32_e32 v31, v4
	v_pk_mul_f32 v[32:33], v[44:45], v[30:31]
	v_add_f32_e32 v26, v26, v27
	v_add_f32_e32 v26, v32, v26
	v_add_f32_e32 v26, v33, v26
	v_mul_f32_e32 v32, 0xbfb8aa3b, v37
	v_exp_f32_e32 v32, v32
	v_mul_f32_e32 v33, 0xbfb8aa3b, v26
	v_exp_f32_e32 v33, v33
; __device__ __forceinline__ float silu_f(float x) { return x * fast_rcp(1.0f + __expf(-x)); }
; __device__ __forceinline__ void delta_unit(const Params& P, LAS unsigned char* lds, int li, bool sample, int b, int h, int half, const int tid) {
;     ...
;                     for (int i = 0; i < 8; ++i) {
;                         float q = cwq[0] * rq[i] + cwq[1] * rq[i + 1] + cwq[2] * rq[i + 2] + cwq[3] * rq[i + 3];
;                         float k = cwk[0] * rk[i] + cwk[1] * rk[i + 1] + cwk[2] * rk[i + 2] + cwk[3] * rk[i + 3];
;                         float v = cwv[0] * rv[i] + cwv[1] * rv[i + 1] + cwv[2] * rv[i + 2] + cwv[3] * rv[i + 3];
;                         q = silu_f(q); k = silu_f(k); v = silu_f(v);
;                         const float sq = wave_sum(q * q), sk = wave_sum(k * k);
;                         const int tok = pw * 8 + i;
;                         qs[tok * 64 + c] = q * rsqrtf(sq + EPS) * 0.125f; ks[tok * 64 + c] = k * rsqrtf(sk + EPS); vs[tok * 64 + c] = v;
;                     }
	v_mul_f32_e32 v27, v11, v52
	v_fmac_f32_e32 v27, v23, v53
	v_add_f32_e32 v32, 1.0, v32
	v_fmac_f32_e32 v27, v72, v55
	v_rcp_f32_e32 v32, v32
	v_add_f32_e32 v33, 1.0, v33
	v_fmac_f32_e32 v27, v73, v54
	v_rcp_f32_e32 v33, v33
	v_mul_f32_e32 v38, 0xbfb8aa3b, v27
	v_exp_f32_e32 v38, v38
	v_mul_f32_e32 v32, v37, v32
	v_mul_f32_e32 v33, v26, v33
	v_mul_f32_e32 v26, v32, v32
	v_add_f32_e32 v38, 1.0, v38
	v_rcp_f32_e32 v38, v38
	v_mov_b32_dpp v26, v26 quad_perm:[1,0,3,2] row_mask:0xf bank_mask:0xf bound_ctrl:1
	v_fmac_f32_e32 v26, v32, v32
	v_mul_f32_e32 v36, v27, v38
	s_nop 0
	v_add_f32_dpp v26, v26, v26 quad_perm:[2,3,0,1] row_mask:0xf bank_mask:0xf bound_ctrl:1
	ds_write2st64_b32 v24, v35, v36 offset0:64 offset1:65
	s_nop 0
	v_add_f32_dpp v26, v26, v26 row_half_mirror row_mask:0xf bank_mask:0xf bound_ctrl:1
	s_nop 1
	v_add_f32_dpp v26, v26, v26 row_mirror row_mask:0xf bank_mask:0xf bound_ctrl:1
	s_nop 0
	v_readlane_b32 s27, v26, 16
	v_readlane_b32 s30, v26, 48
	v_readlane_b32 s0, v26, 0
	v_readlane_b32 s1, v26, 32
	v_mov_b32_e32 v26, s27
	v_mov_b32_e32 v27, s30
	v_pk_add_f32 v[26:27], s[0:1], v[26:27]
	s_nop 0
	v_add_f32_e32 v27, v26, v27
	v_mul_f32_e32 v26, v33, v33
	v_add_f32_e32 v27, 0x358637bd, v27
	v_mul_f32_e32 v37, 0x4b800000, v27
	v_mov_b32_dpp v26, v26 quad_perm:[1,0,3,2] row_mask:0xf bank_mask:0xf bound_ctrl:1
	v_fmac_f32_e32 v26, v33, v33
	v_cmp_gt_f32_e32 vcc, s3, v27
	s_nop 0
	v_add_f32_dpp v26, v26, v26 quad_perm:[2,3,0,1] row_mask:0xf bank_mask:0xf bound_ctrl:1
	v_cndmask_b32_e32 v27, v27, v37, vcc
	v_rsq_f32_e32 v37, v27
	v_add_f32_dpp v26, v26, v26 row_half_mirror row_mask:0xf bank_mask:0xf bound_ctrl:1
	s_nop 1
	v_add_f32_dpp v26, v26, v26 row_mirror row_mask:0xf bank_mask:0xf bound_ctrl:1
	s_nop 0
	v_readlane_b32 s27, v26, 16
	v_readlane_b32 s30, v26, 48
	v_readlane_b32 s0, v26, 0
	v_readlane_b32 s1, v26, 32
	v_mov_b32_e32 v26, s27
	v_mov_b32_e32 v27, s30
	v_pk_add_f32 v[26:27], s[0:1], v[26:27]
	s_nop 0
	v_add_f32_e32 v26, v26, v27
	v_mul_f32_e32 v27, 0x45800000, v37
	v_add_f32_e32 v26, 0x358637bd, v26
	v_cndmask_b32_e32 v27, v37, v27, vcc
	v_mul_f32_e32 v37, 0x4b800000, v26
	v_cmp_gt_f32_e32 vcc, s3, v26
	v_mul_f32_e32 v27, v32, v27
	v_mul_f32_e32 v27, 0x3e000000, v27
	v_cndmask_b32_e32 v26, v26, v37, vcc
	v_rsq_f32_e32 v26, v26
	ds_write2st64_b32 v24, v25, v27 offset1:1
	v_mul_f32_e32 v25, 0x45800000, v26
	v_cndmask_b32_e32 v25, v26, v25, vcc
	v_mul_f32_e32 v25, v33, v25
	v_pk_mul_f32 v[26:27], v[46:47], v[14:15]
	ds_write2st64_b32 v24, v34, v25 offset0:32 offset1:33
	v_pk_mul_f32 v[32:33], v[42:43], v[16:17]
	v_add_f32_e32 v25, v26, v27
	v_add_f32_e32 v25, v32, v25
	v_pk_mul_f32 v[26:27], v[40:41], v[2:3]
	v_add_f32_e32 v25, v33, v25
	v_pk_mul_f32 v[32:33], v[44:45], v[4:5]
	v_add_f32_e32 v26, v26, v27
	v_add_f32_e32 v26, v32, v26
	v_add_f32_e32 v26, v33, v26
	v_mul_f32_e32 v32, 0xbfb8aa3b, v25
	v_exp_f32_e32 v32, v32
	v_mul_f32_e32 v33, 0xbfb8aa3b, v26
	v_exp_f32_e32 v33, v33
	v_mul_f32_e32 v27, v11, v53
	v_fmac_f32_e32 v27, v23, v55
	v_add_f32_e32 v32, 1.0, v32
	v_fmac_f32_e32 v27, v72, v54
	v_rcp_f32_e32 v32, v32
	v_add_f32_e32 v33, 1.0, v33
	v_fmac_f32_e32 v27, v73, v57
	v_rcp_f32_e32 v33, v33
	v_mul_f32_e32 v34, 0xbfb8aa3b, v27
	v_exp_f32_e32 v34, v34
	v_mul_f32_e32 v25, v25, v32
	v_mul_f32_e32 v35, v26, v33
	v_mul_f32_e32 v26, v25, v25
	v_add_f32_e32 v34, 1.0, v34
	v_rcp_f32_e32 v34, v34
	v_mov_b32_dpp v26, v26 quad_perm:[1,0,3,2] row_mask:0xf bank_mask:0xf bound_ctrl:1
	v_fmac_f32_e32 v26, v25, v25
	v_mul_f32_e32 v34, v27, v34
	s_nop 0
	v_add_f32_dpp v26, v26, v26 quad_perm:[2,3,0,1] row_mask:0xf bank_mask:0xf bound_ctrl:1
	s_nop 1
	v_add_f32_dpp v26, v26, v26 row_half_mirror row_mask:0xf bank_mask:0xf bound_ctrl:1
	s_nop 1
	v_add_f32_dpp v26, v26, v26 row_mirror row_mask:0xf bank_mask:0xf bound_ctrl:1
	s_nop 0
	v_readlane_b32 s27, v26, 16
	v_readlane_b32 s30, v26, 48
	v_readlane_b32 s0, v26, 0
	v_readlane_b32 s1, v26, 32
	v_mov_b32_e32 v26, s27
	v_mov_b32_e32 v27, s30
	v_pk_add_f32 v[26:27], s[0:1], v[26:27]
	s_nop 0
	v_add_f32_e32 v27, v26, v27
	v_mul_f32_e32 v26, v35, v35
	v_add_f32_e32 v27, 0x358637bd, v27
	v_mul_f32_e32 v32, 0x4b800000, v27
	v_mov_b32_dpp v26, v26 quad_perm:[1,0,3,2] row_mask:0xf bank_mask:0xf bound_ctrl:1
	v_fmac_f32_e32 v26, v35, v35
	v_cmp_gt_f32_e32 vcc, s3, v27
	s_nop 0
	v_add_f32_dpp v26, v26, v26 quad_perm:[2,3,0,1] row_mask:0xf bank_mask:0xf bound_ctrl:1
	v_cndmask_b32_e32 v27, v27, v32, vcc
	v_rsq_f32_e32 v32, v27
	v_add_f32_dpp v26, v26, v26 row_half_mirror row_mask:0xf bank_mask:0xf bound_ctrl:1
	s_nop 1
	v_add_f32_dpp v26, v26, v26 row_mirror row_mask:0xf bank_mask:0xf bound_ctrl:1
	s_nop 0
	v_readlane_b32 s27, v26, 16
	v_readlane_b32 s30, v26, 48
	v_readlane_b32 s0, v26, 0
	v_readlane_b32 s1, v26, 32
	v_mov_b32_e32 v26, s27
	v_mov_b32_e32 v27, s30
	v_pk_add_f32 v[26:27], s[0:1], v[26:27]
	s_nop 0
	v_add_f32_e32 v26, v26, v27
	v_add_f32_e32 v26, 0x358637bd, v26
	v_mul_f32_e32 v33, 0x4b800000, v26
	v_cmp_gt_f32_e64 s[0:1], s3, v26
	v_mul_f32_e32 v27, 0x45800000, v32
	v_cndmask_b32_e32 v27, v32, v27, vcc
	v_cndmask_b32_e64 v26, v26, v33, s[0:1]
	v_rsq_f32_e32 v26, v26
	v_mul_f32_e32 v25, v25, v27
	v_mul_f32_e32 v25, 0x3e000000, v25
	v_mul_f32_e32 v27, 0x45800000, v26
	v_cndmask_b32_e64 v36, v26, v27, s[0:1]
	v_pk_mul_f32 v[26:27], v[46:47], v[28:29]
	v_mov_b32_e32 v28, v17
	v_mov_b32_e32 v29, v18
	v_pk_mul_f32 v[32:33], v[42:43], v[28:29]
	v_add_f32_e32 v26, v26, v27
	v_add_f32_e32 v26, v32, v26
	v_add_f32_e32 v37, v33, v26
	v_pk_mul_f32 v[26:27], v[40:41], v[30:31]
	v_mov_b32_e32 v30, v5
	v_mov_b32_e32 v31, v6
	v_pk_mul_f32 v[32:33], v[44:45], v[30:31]
	v_add_f32_e32 v26, v26, v27
; __device__ __forceinline__ float silu_f(float x) { return x * fast_rcp(1.0f + __expf(-x)); }
; __device__ __forceinline__ void delta_unit(const Params& P, LAS unsigned char* lds, int li, bool sample, int b, int h, int half, const int tid) {
;     ...
;                     for (int i = 0; i < 8; ++i) {
;                         float q = cwq[0] * rq[i] + cwq[1] * rq[i + 1] + cwq[2] * rq[i + 2] + cwq[3] * rq[i + 3];
;                         float k = cwk[0] * rk[i] + cwk[1] * rk[i + 1] + cwk[2] * rk[i + 2] + cwk[3] * rk[i + 3];
;                         float v = cwv[0] * rv[i] + cwv[1] * rv[i + 1] + cwv[2] * rv[i + 2] + cwv[3] * rv[i + 3];
;                         q = silu_f(q); k = silu_f(k); v = silu_f(v);
;                         const float sq = wave_sum(q * q), sk = wave_sum(k * k);
;                         const int tok = pw * 8 + i;
;                         qs[tok * 64 + c] = q * rsqrtf(sq + EPS) * 0.125f; ks[tok * 64 + c] = k * rsqrtf(sk + EPS); vs[tok * 64 + c] = v;
;                     }
	v_add_f32_e32 v26, v32, v26
	v_add_f32_e32 v26, v33, v26
	v_mul_f32_e32 v32, 0xbfb8aa3b, v37
	v_exp_f32_e32 v32, v32
	v_mul_f32_e32 v33, 0xbfb8aa3b, v26
	v_exp_f32_e32 v33, v33
	v_mul_f32_e32 v27, v11, v55
	v_fmac_f32_e32 v27, v23, v54
	v_add_f32_e32 v32, 1.0, v32
	v_fmac_f32_e32 v27, v72, v57
	v_rcp_f32_e32 v32, v32
	v_add_f32_e32 v33, 1.0, v33
	v_fmac_f32_e32 v27, v73, v56
	v_rcp_f32_e32 v33, v33
	v_mul_f32_e32 v38, 0xbfb8aa3b, v27
	v_exp_f32_e32 v38, v38
	v_mul_f32_e32 v32, v37, v32
	v_mul_f32_e32 v33, v26, v33
	v_mul_f32_e32 v26, v32, v32
	v_add_f32_e32 v38, 1.0, v38
	v_rcp_f32_e32 v38, v38
	v_mov_b32_dpp v26, v26 quad_perm:[1,0,3,2] row_mask:0xf bank_mask:0xf bound_ctrl:1
	v_fmac_f32_e32 v26, v32, v32
	v_mul_f32_e32 v35, v35, v36
	v_mul_f32_e32 v36, v27, v38
	v_add_f32_dpp v26, v26, v26 quad_perm:[2,3,0,1] row_mask:0xf bank_mask:0xf bound_ctrl:1
	ds_write2st64_b32 v24, v34, v36 offset0:66 offset1:67
	s_nop 0
	v_add_f32_dpp v26, v26, v26 row_half_mirror row_mask:0xf bank_mask:0xf bound_ctrl:1
	s_nop 1
	v_add_f32_dpp v26, v26, v26 row_mirror row_mask:0xf bank_mask:0xf bound_ctrl:1
	s_nop 0
	v_readlane_b32 s27, v26, 16
	v_readlane_b32 s30, v26, 48
	v_readlane_b32 s0, v26, 0
	v_readlane_b32 s1, v26, 32
	v_mov_b32_e32 v26, s27
	v_mov_b32_e32 v27, s30
	v_pk_add_f32 v[26:27], s[0:1], v[26:27]
	s_nop 0
	v_add_f32_e32 v27, v26, v27
	v_mul_f32_e32 v26, v33, v33
	v_add_f32_e32 v27, 0x358637bd, v27
	v_mul_f32_e32 v37, 0x4b800000, v27
	v_mov_b32_dpp v26, v26 quad_perm:[1,0,3,2] row_mask:0xf bank_mask:0xf bound_ctrl:1
	v_fmac_f32_e32 v26, v33, v33
	v_cmp_gt_f32_e32 vcc, s3, v27
	s_nop 0
	v_add_f32_dpp v26, v26, v26 quad_perm:[2,3,0,1] row_mask:0xf bank_mask:0xf bound_ctrl:1
	v_cndmask_b32_e32 v27, v27, v37, vcc
	v_rsq_f32_e32 v37, v27
	v_add_f32_dpp v26, v26, v26 row_half_mirror row_mask:0xf bank_mask:0xf bound_ctrl:1
	s_nop 1
	v_add_f32_dpp v26, v26, v26 row_mirror row_mask:0xf bank_mask:0xf bound_ctrl:1
	s_nop 0
	v_readlane_b32 s27, v26, 16
	v_readlane_b32 s30, v26, 48
	v_readlane_b32 s0, v26, 0
	v_readlane_b32 s1, v26, 32
	v_mov_b32_e32 v26, s27
	v_mov_b32_e32 v27, s30
	v_pk_add_f32 v[26:27], s[0:1], v[26:27]
	s_nop 0
	v_add_f32_e32 v26, v26, v27
	v_mul_f32_e32 v27, 0x45800000, v37
	v_add_f32_e32 v26, 0x358637bd, v26
	v_cndmask_b32_e32 v27, v37, v27, vcc
	v_mul_f32_e32 v37, 0x4b800000, v26
	v_cmp_gt_f32_e32 vcc, s3, v26
	v_mul_f32_e32 v27, v32, v27
	v_mul_f32_e32 v27, 0x3e000000, v27
	v_cndmask_b32_e32 v26, v26, v37, vcc
	v_rsq_f32_e32 v26, v26
	ds_write2st64_b32 v24, v25, v27 offset0:2 offset1:3
	v_mul_f32_e32 v25, 0x45800000, v26
	v_cndmask_b32_e32 v25, v26, v25, vcc
	v_mul_f32_e32 v25, v33, v25
	v_pk_mul_f32 v[26:27], v[46:47], v[16:17]
	ds_write2st64_b32 v24, v35, v25 offset0:34 offset1:35
	v_pk_mul_f32 v[32:33], v[42:43], v[18:19]
	v_add_f32_e32 v25, v26, v27
	v_add_f32_e32 v25, v32, v25
	v_pk_mul_f32 v[26:27], v[40:41], v[4:5]
	v_add_f32_e32 v25, v33, v25
	v_pk_mul_f32 v[32:33], v[44:45], v[6:7]
	v_add_f32_e32 v26, v26, v27
	v_add_f32_e32 v26, v32, v26
	v_add_f32_e32 v26, v33, v26
	v_mul_f32_e32 v32, 0xbfb8aa3b, v25
	v_exp_f32_e32 v32, v32
	v_mul_f32_e32 v33, 0xbfb8aa3b, v26
	v_exp_f32_e32 v33, v33
	v_mul_f32_e32 v27, v11, v54
	v_fmac_f32_e32 v27, v23, v57
	v_add_f32_e32 v32, 1.0, v32
	v_fmac_f32_e32 v27, v72, v56
	v_rcp_f32_e32 v32, v32
	v_add_f32_e32 v33, 1.0, v33
	v_fmac_f32_e32 v27, v73, v59
	v_rcp_f32_e32 v33, v33
	v_mul_f32_e32 v35, 0xbfb8aa3b, v27
	v_exp_f32_e32 v35, v35
	v_mul_f32_e32 v25, v25, v32
	v_mul_f32_e32 v34, v26, v33
	v_mul_f32_e32 v26, v25, v25
	v_add_f32_e32 v35, 1.0, v35
	v_rcp_f32_e32 v35, v35
	v_mov_b32_dpp v26, v26 quad_perm:[1,0,3,2] row_mask:0xf bank_mask:0xf bound_ctrl:1
	v_fmac_f32_e32 v26, v25, v25
	v_mul_f32_e32 v35, v27, v35
	s_nop 0
	v_add_f32_dpp v26, v26, v26 quad_perm:[2,3,0,1] row_mask:0xf bank_mask:0xf bound_ctrl:1
	s_nop 1
	v_add_f32_dpp v26, v26, v26 row_half_mirror row_mask:0xf bank_mask:0xf bound_ctrl:1
	s_nop 1
	v_add_f32_dpp v26, v26, v26 row_mirror row_mask:0xf bank_mask:0xf bound_ctrl:1
	s_nop 0
	v_readlane_b32 s27, v26, 16
	v_readlane_b32 s30, v26, 48
	v_readlane_b32 s0, v26, 0
	v_readlane_b32 s1, v26, 32
	v_mov_b32_e32 v26, s27
	v_mov_b32_e32 v27, s30
	v_pk_add_f32 v[26:27], s[0:1], v[26:27]
	s_nop 0
	v_add_f32_e32 v27, v26, v27
	v_mul_f32_e32 v26, v34, v34
	v_add_f32_e32 v27, 0x358637bd, v27
	v_mul_f32_e32 v32, 0x4b800000, v27
	v_mov_b32_dpp v26, v26 quad_perm:[1,0,3,2] row_mask:0xf bank_mask:0xf bound_ctrl:1
	v_fmac_f32_e32 v26, v34, v34
	v_cmp_gt_f32_e32 vcc, s3, v27
	s_nop 0
	v_add_f32_dpp v26, v26, v26 quad_perm:[2,3,0,1] row_mask:0xf bank_mask:0xf bound_ctrl:1
	v_cndmask_b32_e32 v27, v27, v32, vcc
	v_rsq_f32_e32 v32, v27
	v_add_f32_dpp v26, v26, v26 row_half_mirror row_mask:0xf bank_mask:0xf bound_ctrl:1
	s_nop 1
	v_add_f32_dpp v26, v26, v26 row_mirror row_mask:0xf bank_mask:0xf bound_ctrl:1
	s_nop 0
	v_readlane_b32 s27, v26, 16
	v_readlane_b32 s30, v26, 48
	v_readlane_b32 s0, v26, 0
	v_readlane_b32 s1, v26, 32
	v_mov_b32_e32 v26, s27
	v_mov_b32_e32 v27, s30
	v_pk_add_f32 v[26:27], s[0:1], v[26:27]
	s_nop 0
	v_add_f32_e32 v26, v26, v27
	v_add_f32_e32 v26, 0x358637bd, v26
	v_mul_f32_e32 v33, 0x4b800000, v26
	v_cmp_gt_f32_e64 s[0:1], s3, v26
	v_mul_f32_e32 v27, 0x45800000, v32
	v_cndmask_b32_e32 v27, v32, v27, vcc
	v_cndmask_b32_e64 v26, v26, v33, s[0:1]
	v_rsq_f32_e32 v26, v26
	v_mul_f32_e32 v25, v25, v27
	v_mul_f32_e32 v25, 0x3e000000, v25
	v_mul_f32_e32 v27, 0x45800000, v26
	v_cndmask_b32_e64 v36, v26, v27, s[0:1]
	v_pk_mul_f32 v[26:27], v[46:47], v[28:29]
	v_mov_b32_e32 v28, v19
	v_mov_b32_e32 v29, v20
	v_pk_mul_f32 v[32:33], v[42:43], v[28:29]
	v_add_f32_e32 v26, v26, v27
; __device__ __forceinline__ float silu_f(float x) { return x * fast_rcp(1.0f + __expf(-x)); }
; __device__ __forceinline__ void delta_unit(const Params& P, LAS unsigned char* lds, int li, bool sample, int b, int h, int half, const int tid) {
;     ...
;                     for (int i = 0; i < 8; ++i) {
;                         float q = cwq[0] * rq[i] + cwq[1] * rq[i + 1] + cwq[2] * rq[i + 2] + cwq[3] * rq[i + 3];
;                         float k = cwk[0] * rk[i] + cwk[1] * rk[i + 1] + cwk[2] * rk[i + 2] + cwk[3] * rk[i + 3];
;                         float v = cwv[0] * rv[i] + cwv[1] * rv[i + 1] + cwv[2] * rv[i + 2] + cwv[3] * rv[i + 3];
;                         q = silu_f(q); k = silu_f(k); v = silu_f(v);
;                         const float sq = wave_sum(q * q), sk = wave_sum(k * k);
;                         const int tok = pw * 8 + i;
;                         qs[tok * 64 + c] = q * rsqrtf(sq + EPS) * 0.125f; ks[tok * 64 + c] = k * rsqrtf(sk + EPS); vs[tok * 64 + c] = v;
;                     }
	v_add_f32_e32 v26, v32, v26
	v_add_f32_e32 v37, v33, v26
	v_pk_mul_f32 v[26:27], v[40:41], v[30:31]
	v_mov_b32_e32 v30, v7
	v_mov_b32_e32 v31, v8
	v_pk_mul_f32 v[32:33], v[44:45], v[30:31]
	v_add_f32_e32 v26, v26, v27
	v_add_f32_e32 v26, v32, v26
	v_add_f32_e32 v26, v33, v26
	v_mul_f32_e32 v32, 0xbfb8aa3b, v37
	v_exp_f32_e32 v32, v32
	v_mul_f32_e32 v33, 0xbfb8aa3b, v26
	v_exp_f32_e32 v33, v33
	v_mul_f32_e32 v27, v11, v57
	v_fmac_f32_e32 v27, v23, v56
	v_add_f32_e32 v32, 1.0, v32
	v_fmac_f32_e32 v27, v72, v59
	v_rcp_f32_e32 v32, v32
	v_add_f32_e32 v33, 1.0, v33
	v_fmac_f32_e32 v27, v73, v58
	v_rcp_f32_e32 v33, v33
	v_mul_f32_e32 v38, 0xbfb8aa3b, v27
	v_exp_f32_e32 v38, v38
	v_mul_f32_e32 v32, v37, v32
	v_mul_f32_e32 v33, v26, v33
	v_mul_f32_e32 v26, v32, v32
	v_add_f32_e32 v38, 1.0, v38
	v_rcp_f32_e32 v38, v38
	v_mov_b32_dpp v26, v26 quad_perm:[1,0,3,2] row_mask:0xf bank_mask:0xf bound_ctrl:1
	v_fmac_f32_e32 v26, v32, v32
	v_mul_f32_e32 v34, v34, v36
	v_mul_f32_e32 v36, v27, v38
	v_add_f32_dpp v26, v26, v26 quad_perm:[2,3,0,1] row_mask:0xf bank_mask:0xf bound_ctrl:1
	ds_write2st64_b32 v24, v35, v36 offset0:68 offset1:69
	s_nop 0
	v_add_f32_dpp v26, v26, v26 row_half_mirror row_mask:0xf bank_mask:0xf bound_ctrl:1
	s_nop 1
	v_add_f32_dpp v26, v26, v26 row_mirror row_mask:0xf bank_mask:0xf bound_ctrl:1
	s_nop 0
	v_readlane_b32 s27, v26, 16
	v_readlane_b32 s30, v26, 48
	v_readlane_b32 s0, v26, 0
	v_readlane_b32 s1, v26, 32
	v_mov_b32_e32 v26, s27
	v_mov_b32_e32 v27, s30
	v_pk_add_f32 v[26:27], s[0:1], v[26:27]
	s_nop 0
	v_add_f32_e32 v27, v26, v27
	v_mul_f32_e32 v26, v33, v33
	v_add_f32_e32 v27, 0x358637bd, v27
	v_mul_f32_e32 v37, 0x4b800000, v27
	v_mov_b32_dpp v26, v26 quad_perm:[1,0,3,2] row_mask:0xf bank_mask:0xf bound_ctrl:1
	v_fmac_f32_e32 v26, v33, v33
	v_cmp_gt_f32_e32 vcc, s3, v27
	s_nop 0
	v_add_f32_dpp v26, v26, v26 quad_perm:[2,3,0,1] row_mask:0xf bank_mask:0xf bound_ctrl:1
	v_cndmask_b32_e32 v27, v27, v37, vcc
	v_rsq_f32_e32 v37, v27
	v_add_f32_dpp v26, v26, v26 row_half_mirror row_mask:0xf bank_mask:0xf bound_ctrl:1
	s_nop 1
	v_add_f32_dpp v26, v26, v26 row_mirror row_mask:0xf bank_mask:0xf bound_ctrl:1
	s_nop 0
	v_readlane_b32 s27, v26, 16
	v_readlane_b32 s30, v26, 48
	v_readlane_b32 s0, v26, 0
	v_readlane_b32 s1, v26, 32
	v_mov_b32_e32 v26, s27
	v_mov_b32_e32 v27, s30
	v_pk_add_f32 v[26:27], s[0:1], v[26:27]
	s_nop 0
	v_add_f32_e32 v26, v26, v27
	v_mul_f32_e32 v27, 0x45800000, v37
	v_add_f32_e32 v26, 0x358637bd, v26
	v_cndmask_b32_e32 v27, v37, v27, vcc
	v_mul_f32_e32 v37, 0x4b800000, v26
	v_cmp_gt_f32_e32 vcc, s3, v26
	v_mul_f32_e32 v27, v32, v27
	v_mul_f32_e32 v27, 0x3e000000, v27
	v_cndmask_b32_e32 v26, v26, v37, vcc
	v_rsq_f32_e32 v26, v26
	ds_write2st64_b32 v24, v25, v27 offset0:4 offset1:5
	v_mul_f32_e32 v25, 0x45800000, v26
	v_cndmask_b32_e32 v25, v26, v25, vcc
	v_mul_f32_e32 v25, v33, v25
	v_pk_mul_f32 v[26:27], v[46:47], v[18:19]
	ds_write2st64_b32 v24, v34, v25 offset0:36 offset1:37
	v_pk_mul_f32 v[32:33], v[42:43], v[20:21]
	v_add_f32_e32 v25, v26, v27
	v_add_f32_e32 v25, v32, v25
	v_pk_mul_f32 v[26:27], v[40:41], v[6:7]
	v_add_f32_e32 v25, v33, v25
	v_pk_mul_f32 v[32:33], v[44:45], v[8:9]
	v_add_f32_e32 v26, v26, v27
	v_add_f32_e32 v26, v32, v26
	v_add_f32_e32 v26, v33, v26
	v_mul_f32_e32 v32, 0xbfb8aa3b, v25
	v_exp_f32_e32 v32, v32
	v_mul_f32_e32 v33, 0xbfb8aa3b, v26
	v_exp_f32_e32 v33, v33
	v_mul_f32_e32 v27, v11, v56
	v_fmac_f32_e32 v27, v23, v59
	v_add_f32_e32 v32, 1.0, v32
	v_fmac_f32_e32 v27, v72, v58
	v_rcp_f32_e32 v32, v32
	v_add_f32_e32 v33, 1.0, v33
	v_fmac_f32_e32 v27, v73, v61
	v_rcp_f32_e32 v33, v33
	v_mul_f32_e32 v34, 0xbfb8aa3b, v27
	v_exp_f32_e32 v34, v34
	v_mul_f32_e32 v25, v25, v32
	v_mul_f32_e32 v32, v26, v33
	v_mul_f32_e32 v26, v25, v25
	v_add_f32_e32 v34, 1.0, v34
	v_rcp_f32_e32 v34, v34
	v_mov_b32_dpp v26, v26 quad_perm:[1,0,3,2] row_mask:0xf bank_mask:0xf bound_ctrl:1
	v_fmac_f32_e32 v26, v25, v25
	v_mul_f32_e32 v33, v27, v34
	s_nop 0
	v_add_f32_dpp v26, v26, v26 quad_perm:[2,3,0,1] row_mask:0xf bank_mask:0xf bound_ctrl:1
	s_nop 1
	v_add_f32_dpp v26, v26, v26 row_half_mirror row_mask:0xf bank_mask:0xf bound_ctrl:1
	s_nop 1
	v_add_f32_dpp v26, v26, v26 row_mirror row_mask:0xf bank_mask:0xf bound_ctrl:1
	s_nop 0
	v_readlane_b32 s27, v26, 16
	v_readlane_b32 s30, v26, 48
	v_readlane_b32 s0, v26, 0
	v_readlane_b32 s1, v26, 32
	v_mov_b32_e32 v26, s27
	v_mov_b32_e32 v27, s30
	v_pk_add_f32 v[26:27], s[0:1], v[26:27]
	s_nop 0
	v_add_f32_e32 v27, v26, v27
	v_mul_f32_e32 v26, v32, v32
	v_add_f32_e32 v27, 0x358637bd, v27
	v_mul_f32_e32 v34, 0x4b800000, v27
	v_mov_b32_dpp v26, v26 quad_perm:[1,0,3,2] row_mask:0xf bank_mask:0xf bound_ctrl:1
	v_fmac_f32_e32 v26, v32, v32
	v_cmp_gt_f32_e32 vcc, s3, v27
	s_nop 0
	v_add_f32_dpp v26, v26, v26 quad_perm:[2,3,0,1] row_mask:0xf bank_mask:0xf bound_ctrl:1
	v_cndmask_b32_e32 v27, v27, v34, vcc
	v_rsq_f32_e32 v34, v27
; __device__ __forceinline__ float silu_f(float x) { return x * fast_rcp(1.0f + __expf(-x)); }
; __device__ __forceinline__ float sigmoid_f(float x) { return fast_rcp(1.0f + __expf(-x)); }
; __device__ __forceinline__ float softplus_f(float x) { return fmaxf(x, 0.f) + __logf(1.0f + __expf(-fabsf(x))); }
; __device__ __forceinline__ void delta_unit(const Params& P, LAS unsigned char* lds, int li, bool sample, int b, int h, int half, const int tid) {
;     ...
;                     for (int i = 0; i < 8; ++i) {
;                         float q = cwq[0] * rq[i] + cwq[1] * rq[i + 1] + cwq[2] * rq[i + 2] + cwq[3] * rq[i + 3];
;                         float k = cwk[0] * rk[i] + cwk[1] * rk[i + 1] + cwk[2] * rk[i + 2] + cwk[3] * rk[i + 3];
;                         float v = cwv[0] * rv[i] + cwv[1] * rv[i + 1] + cwv[2] * rv[i + 2] + cwv[3] * rv[i + 3];
;                         q = silu_f(q); k = silu_f(k); v = silu_f(v);
;                         const float sq = wave_sum(q * q), sk = wave_sum(k * k);
;                         const int tok = pw * 8 + i;
;                         qs[tok * 64 + c] = q * rsqrtf(sq + EPS) * 0.125f; ks[tok * 64 + c] = k * rsqrtf(sk + EPS); vs[tok * 64 + c] = v;
;                     }
;                     if (lane < 8) { const float g = -__expf(alog) * softplus_f(ga + dtb); sc[(pw * 8 + lane) * 2] = __expf(g); sc[(pw * 8 + lane) * 2 + 1] = sigmoid_f(gb_); }
	v_add_f32_dpp v26, v26, v26 row_half_mirror row_mask:0xf bank_mask:0xf bound_ctrl:1
	s_nop 1
	v_add_f32_dpp v26, v26, v26 row_mirror row_mask:0xf bank_mask:0xf bound_ctrl:1
	s_nop 0
	v_readlane_b32 s27, v26, 16
	v_readlane_b32 s30, v26, 48
	v_readlane_b32 s0, v26, 0
	v_readlane_b32 s1, v26, 32
	v_mov_b32_e32 v26, s27
	v_mov_b32_e32 v27, s30
	v_pk_add_f32 v[26:27], s[0:1], v[26:27]
	s_nop 0
	v_add_f32_e32 v26, v26, v27
	v_add_f32_e32 v26, 0x358637bd, v26
	v_mul_f32_e32 v35, 0x4b800000, v26
	v_cmp_gt_f32_e64 s[0:1], s3, v26
	v_mul_f32_e32 v27, 0x45800000, v34
	v_cndmask_b32_e32 v27, v34, v27, vcc
	v_cndmask_b32_e64 v26, v26, v35, s[0:1]
	v_rsq_f32_e32 v26, v26
	v_mul_f32_e32 v25, v25, v27
	v_mul_f32_e32 v25, 0x3e000000, v25
	v_mul_f32_e32 v27, 0x45800000, v26
	v_cndmask_b32_e64 v34, v26, v27, s[0:1]
	v_pk_mul_f32 v[26:27], v[46:47], v[28:29]
	v_mov_b32_e32 v28, v21
	v_mov_b32_e32 v29, v22
	v_pk_mul_f32 v[28:29], v[42:43], v[28:29]
	v_add_f32_e32 v26, v26, v27
	v_add_f32_e32 v26, v28, v26
	v_add_f32_e32 v35, v29, v26
	v_pk_mul_f32 v[26:27], v[40:41], v[30:31]
	v_mov_b32_e32 v28, v9
	v_mov_b32_e32 v29, v10
	v_pk_mul_f32 v[28:29], v[44:45], v[28:29]
	v_add_f32_e32 v26, v26, v27
	v_add_f32_e32 v26, v28, v26
	v_add_f32_e32 v26, v29, v26
	v_mul_f32_e32 v28, 0xbfb8aa3b, v35
	v_exp_f32_e32 v28, v28
	v_mul_f32_e32 v29, 0xbfb8aa3b, v26
	v_exp_f32_e32 v29, v29
	v_mul_f32_e32 v27, v11, v59
	v_fmac_f32_e32 v27, v23, v58
	v_add_f32_e32 v28, 1.0, v28
	v_fmac_f32_e32 v27, v72, v61
	v_rcp_f32_e32 v28, v28
	v_add_f32_e32 v29, 1.0, v29
	v_fmac_f32_e32 v27, v73, v60
	v_rcp_f32_e32 v29, v29
	v_mul_f32_e32 v30, 0xbfb8aa3b, v27
	v_exp_f32_e32 v30, v30
	v_mul_f32_e32 v28, v35, v28
	v_mul_f32_e32 v29, v26, v29
	v_mul_f32_e32 v26, v28, v28
	v_add_f32_e32 v30, 1.0, v30
	v_rcp_f32_e32 v30, v30
	v_mov_b32_dpp v26, v26 quad_perm:[1,0,3,2] row_mask:0xf bank_mask:0xf bound_ctrl:1
	v_fmac_f32_e32 v26, v28, v28
	v_mul_f32_e32 v31, v32, v34
	v_mul_f32_e32 v30, v27, v30
	v_add_f32_dpp v26, v26, v26 quad_perm:[2,3,0,1] row_mask:0xf bank_mask:0xf bound_ctrl:1
	s_nop 1
	v_add_f32_dpp v26, v26, v26 row_half_mirror row_mask:0xf bank_mask:0xf bound_ctrl:1
	s_nop 1
	v_add_f32_dpp v26, v26, v26 row_mirror row_mask:0xf bank_mask:0xf bound_ctrl:1
	s_nop 0
	v_readlane_b32 s27, v26, 16
	v_readlane_b32 s30, v26, 48
	v_readlane_b32 s0, v26, 0
	v_readlane_b32 s1, v26, 32
	v_mov_b32_e32 v26, s27
	v_mov_b32_e32 v27, s30
	v_pk_add_f32 v[26:27], s[0:1], v[26:27]
	s_nop 0
	v_add_f32_e32 v27, v26, v27
	v_mul_f32_e32 v26, v29, v29
	v_add_f32_e32 v27, 0x358637bd, v27
	v_mul_f32_e32 v32, 0x4b800000, v27
	v_mov_b32_dpp v26, v26 quad_perm:[1,0,3,2] row_mask:0xf bank_mask:0xf bound_ctrl:1
	v_fmac_f32_e32 v26, v29, v29
	v_cmp_gt_f32_e32 vcc, s3, v27
	s_nop 0
	v_add_f32_dpp v26, v26, v26 quad_perm:[2,3,0,1] row_mask:0xf bank_mask:0xf bound_ctrl:1
	v_cndmask_b32_e32 v27, v27, v32, vcc
	v_rsq_f32_e32 v32, v27
	v_add_f32_dpp v26, v26, v26 row_half_mirror row_mask:0xf bank_mask:0xf bound_ctrl:1
	s_nop 1
	v_add_f32_dpp v26, v26, v26 row_mirror row_mask:0xf bank_mask:0xf bound_ctrl:1
	s_nop 0
	v_readlane_b32 s27, v26, 16
	v_readlane_b32 s30, v26, 48
	v_readlane_b32 s0, v26, 0
	v_readlane_b32 s1, v26, 32
	v_mov_b32_e32 v26, s27
	v_mov_b32_e32 v27, s30
	v_pk_add_f32 v[26:27], s[0:1], v[26:27]
	s_nop 0
	v_add_f32_e32 v26, v26, v27
	v_mul_f32_e32 v27, 0x45800000, v32
	v_add_f32_e32 v26, 0x358637bd, v26
	v_cndmask_b32_e32 v27, v32, v27, vcc
	v_mul_f32_e32 v32, 0x4b800000, v26
	v_cmp_gt_f32_e32 vcc, s3, v26
	v_mul_f32_e32 v27, v28, v27
	v_mul_f32_e32 v27, 0x3e000000, v27
	v_cndmask_b32_e32 v26, v26, v32, vcc
	v_rsq_f32_e32 v26, v26
	ds_write2st64_b32 v24, v25, v27 offset0:6 offset1:7
	v_mul_f32_e32 v25, 0x45800000, v26
	v_cndmask_b32_e32 v25, v26, v25, vcc
	v_mul_f32_e32 v25, v29, v25
	ds_write2st64_b32 v24, v31, v25 offset0:38 offset1:39
	ds_write2st64_b32 v24, v33, v30 offset0:70 offset1:71
	s_and_saveexec_b64 s[0:1], s[38:39]
	s_cbranch_execz .LBB0_659
	s_waitcnt vmcnt(1)
	v_add_f32_e32 v24, v74, v93
	s_mov_b32 s27, 0xbfb8aa3b
	v_mul_f32_e64 v25, |v24|, s27
	v_exp_f32_e32 v25, v25
	s_mov_b32 s27, 0x3f317217
	s_waitcnt vmcnt(0)
	v_mul_f32_e32 v26, 0xbfb8aa3b, v94
	v_exp_f32_e32 v26, v26
	v_add_f32_e32 v25, 1.0, v25
	v_cmp_gt_f32_e32 vcc, s3, v25
	v_max_f32_e32 v24, 0, v24
	v_add_f32_e32 v26, 1.0, v26
	v_cndmask_b32_e64 v27, 0, 32, vcc
	v_ldexp_f32 v25, v25, v27
	v_log_f32_e32 v25, v25
	v_cndmask_b32_e32 v27, 0, v204, vcc
	v_mul_f32_e32 v28, 0x3f317217, v25
	v_fma_f32 v28, v25, s27, -v28
	v_fmac_f32_e32 v28, 0x3377d1cf, v25
	s_mov_b32 s27, 0x7f800000
	v_fmac_f32_e32 v28, 0x3f317217, v25
	v_cmp_lt_f32_e64 vcc, |v25|, s27
	s_nop 1
	v_cndmask_b32_e32 v25, v25, v28, vcc
	v_sub_f32_e32 v25, v25, v27
	v_add_f32_e32 v24, v24, v25
	v_mul_f32_e32 v24, v24, v79
	v_mul_f32_e32 v24, 0xbfb8aa3b, v24
	v_exp_f32_e32 v24, v24
	v_rcp_f32_e32 v25, v26
	v_add_u32_e32 v26, s26, v80
	ds_write_b64 v26, v[24:25] offset:32768

; #define LAS __attribute__((address_space(3)))
; __device__ __forceinline__ unsigned f2bf(float f) { unsigned u = __builtin_bit_cast(unsigned, f); return (u + 0x7fffu + ((u >> 16) & 1u)) >> 16; }
; __device__ __forceinline__ void delta_unit(const Params& P, LAS unsigned char* lds, int li, bool sample, int b, int h, int half, const int tid) {
;     ...
;             if (j >= 2) {
;                 LAS float* os = (LAS float*)(lds + (j & 1) * SET) + 6144;
;                 const int t0 = (j - 2) * MX_CH + pw * 8;
;                 if (t0 < L && (c >> 5) == half) {
; #pragma unroll
;                     for (int i = 0; i < 8; ++i) {
;                         const int tok = pw * 8 + i; const size_t row = (size_t)(rowbase + t0 + i);
;                         MIX[row * DM + h * 64 + c] = (bf16_t)f2bf(os[tok * 64 + c]);
;                     }
;                 }
;             }
.LBB0_662:
	s_cmp_lt_u32 s14, 2
	s_cbranch_scc1 .LBB0_667
	s_addk_i32 s25, 0xffa0
	s_cmpk_lt_i32 s25, 0x1000
	s_cselect_b64 s[0:1], -1, 0
	s_and_b64 s[26:27], s[40:41], s[0:1]
	s_and_saveexec_b64 s[0:1], s[26:27]
	s_cbranch_execz .LBB0_665
	s_bitcmp1_b32 s14, 0
	s_cselect_b32 s26, 0x8100, 0
	s_waitcnt lgkmcnt(3)
	v_add_u32_e32 v130, s26, v85
	ds_read2st64_b32 v[124:125], v130 offset0:96 offset1:97
	s_add_i32 s34, s25, s13
	s_ashr_i32 s35, s34, 31
	s_movk_i32 s25, 0x7fff
	s_lshl_b64 s[26:27], s[34:35], 11
	s_waitcnt lgkmcnt(0)
	v_bfe_u32 v132, v124, 16, 1
	v_add3_u32 v124, v124, v132, s25
	v_lshl_add_u64 v[132:133], v[50:51], 0, s[26:27]
	s_or_b32 s26, s34, 1
	s_ashr_i32 s27, s26, 31
	ds_read2st64_b32 v[126:127], v130 offset0:98 offset1:99
	ds_read2st64_b32 v[128:129], v130 offset0:100 offset1:101
	ds_read2st64_b32 v[130:131], v130 offset0:102 offset1:103
	global_store_short_d16_hi v[132:133], v124, off
	v_bfe_u32 v124, v125, 16, 1
	s_lshl_b64 s[26:27], s[26:27], 11
	v_add3_u32 v132, v125, v124, s25
	v_lshl_add_u64 v[124:125], v[50:51], 0, s[26:27]
	s_or_b32 s26, s34, 2
	s_ashr_i32 s27, s26, 31
	global_store_short_d16_hi v[124:125], v132, off
	s_waitcnt lgkmcnt(2)
	v_bfe_u32 v124, v126, 16, 1
	s_lshl_b64 s[26:27], s[26:27], 11
	v_add3_u32 v126, v126, v124, s25
	v_lshl_add_u64 v[124:125], v[50:51], 0, s[26:27]
	s_or_b32 s26, s34, 3
	s_ashr_i32 s27, s26, 31
	global_store_short_d16_hi v[124:125], v126, off
	v_bfe_u32 v124, v127, 16, 1
	s_lshl_b64 s[26:27], s[26:27], 11
	v_add3_u32 v126, v127, v124, s25
	v_lshl_add_u64 v[124:125], v[50:51], 0, s[26:27]
	s_or_b32 s26, s34, 4
	s_ashr_i32 s27, s26, 31
	global_store_short_d16_hi v[124:125], v126, off
	s_waitcnt lgkmcnt(1)
	v_bfe_u32 v124, v128, 16, 1
	s_lshl_b64 s[26:27], s[26:27], 11
	v_add3_u32 v126, v128, v124, s25
	v_lshl_add_u64 v[124:125], v[50:51], 0, s[26:27]
	s_or_b32 s26, s34, 5
	s_ashr_i32 s27, s26, 31
	global_store_short_d16_hi v[124:125], v126, off
	v_bfe_u32 v124, v129, 16, 1
	s_lshl_b64 s[26:27], s[26:27], 11
	v_add3_u32 v126, v129, v124, s25
	v_lshl_add_u64 v[124:125], v[50:51], 0, s[26:27]
	s_or_b32 s26, s34, 6
	s_ashr_i32 s27, s26, 31
	global_store_short_d16_hi v[124:125], v126, off
	s_waitcnt lgkmcnt(0)
	v_bfe_u32 v124, v130, 16, 1
	s_lshl_b64 s[26:27], s[26:27], 11
	v_add3_u32 v126, v130, v124, s25
	v_lshl_add_u64 v[124:125], v[50:51], 0, s[26:27]
	s_or_b32 s26, s34, 7
	s_ashr_i32 s27, s26, 31
	global_store_short_d16_hi v[124:125], v126, off
	v_bfe_u32 v124, v131, 16, 1
	s_lshl_b64 s[26:27], s[26:27], 11
	v_add3_u32 v126, v131, v124, s25
	v_lshl_add_u64 v[124:125], v[50:51], 0, s[26:27]
	global_store_short_d16_hi v[124:125], v126, off
